# k31 + attention tile loop back-edge rotation (ring rotation and loop test moved above the closing barrier, single conditional back-branch) + grid barrier pointer s_load issued before the L2 writeback
# baseline (speedup 1.0000x reference)
; __global__ void __launch_bounds__(NWAVES * 64, 2) mega_fwd(Args args) {
;     ...
;         if (ph > lo) { if (hi > (1 << 20)) cg::this_grid().sync(); else xcd_barrier(xbar); }
.LBB0_70:
	s_and_b64 vcc, exec, s[0:1]
	s_cbranch_vccz .LBB0_82
	s_barrier
	s_mov_b64 s[0:1], exec
	v_readlane_b32 s4, v255, 21
	v_readlane_b32 s5, v255, 22
	s_and_b64 s[4:5], s[0:1], s[4:5]
	s_mov_b64 exec, s[4:5]
	s_cbranch_execz .LBB0_81
	v_readlane_b32 s4, v254, 5
	v_readlane_b32 s5, v254, 6
	s_nop 4
	s_load_dwordx2 s[4:5], s[4:5], 0x58
	buffer_wbl2 sc1
	s_waitcnt vmcnt(0)
	s_mov_b64 s[6:7], exec
	v_mbcnt_lo_u32_b32 v1, s6, 0
	v_mbcnt_hi_u32_b32 v1, s7, v1
	v_cmp_eq_u32_e32 vcc, 0, v1
	s_waitcnt lgkmcnt(0)
	global_load_dword v0, v211, s[4:5] offset:40
	s_and_saveexec_b64 s[10:11], vcc
	s_cbranch_execz .LBB0_74
	s_bcnt1_i32_b64 s6, s[6:7]
	v_mov_b32_e32 v2, s6
	global_atomic_add v2, v211, v2, s[4:5] offset:32 sc0

; #define AT_LOAD(t_, S) do { const int tc_ = (t_) < NT ? (t_) : NT - 1; const size_t off_ = (size_t)tc_ * 64; k0r##S = *(const u32x4*)(kg0 + off_ * 768); k1r##S = *(const u32x4*)(kg1 + off_ * 768); vr##S = *(const u32x4*)(vg + off_ * 512); } while (0)
; #define AT_STORE(bo_, S) do { unsigned char* lb_ = lds + (bo_); *(u32x4*)(lb_ + ks0) = k0r##S; if (tid < 256) *(u32x4*)(lb_ + ks1) = k1r##S; *(u32x4*)(lb_ + vs0) = vr##S; } while (0)
; __device__ __forceinline__ void attn_unit(const Ctx& c, int bh, int qb, const bf16_t* Q, const bf16_t* Kb, const bf16_t* Vb, bf16_t* O) {
;     ...
;     int b0 = 0, b1 = AT_BUF, b2 = 2 * AT_BUF;
;     float mrow = -1e30f, lsum = 0.f;
;     f32x16 o[2]; o[0] = f32x16{}; o[1] = f32x16{};
;     AT_LOAD(0, A); AT_LOAD(1, B); AT_STORE(b0, A); AT_LOAD(2, A); AT_STORE(b1, B); AT_LOAD(3, B);
;     __syncthreads();
;     f32x16 pA0, pA1, pB0, pB1;
;     AT_QK(pA0, pA1, b0);
;     for (int t = 0; t < NT; t += 2) {
;         AT_STEP(pA0, pA1, pB0, pB1, t, A);
;         AT_STEP(pB0, pB1, pA0, pA1, t + 1, B);
.LBB0_310:
	s_add_i32 s13, s13, 2
	s_mov_b32 s56, s12
	s_mov_b32 s12, s25
	s_cmp_ge_u32 s13, s8
	s_waitcnt lgkmcnt(0)
	s_barrier
	s_cbranch_scc0 .LBB0_290
